# one 4-byte s_nop inserted after the FFT phase (placement shift of the phase-13 entry code)
# baseline (speedup 1.0000x reference)
.LBB0_238:
	s_mov_b64 s[0:1], 0
	s_nop 0
